# GDN output-norm queue items hand-written: 256 items of 256 rows, all loads of an item issued up front with counted vmcnt, DPP row reduction
# speedup vs baseline: 1.0361x; 1.0229x over previous
.LBB0_575:
	s_or_b64 exec, exec, s[4:5]
	v_mov_b32_e32 v0, s85
	s_waitcnt lgkmcnt(0)
	s_barrier
	ds_read_b32 v0, v0
	s_waitcnt lgkmcnt(0)
	s_barrier
	v_readfirstlane_b32 s28, v0
	s_cmpk_gt_i32 s28, 0x37f
	s_cselect_b64 s[54:55], -1, 0
	s_and_b64 vcc, exec, s[54:55]
	s_cbranch_vccnz .LBB0_572
	s_and_saveexec_b64 s[4:5], s[38:39]
	s_cbranch_execz .LBB0_579
	v_mov_b64_e32 v[0:1], s[92:93]
	s_waitcnt vmcnt(0)
	flat_atomic_add v78, v[0:1], v230 sc0
	s_or_b64 exec, exec, s[4:5]
	s_cmpk_gt_i32 s28, 0xff
	s_mov_b64 s[4:5], -1
	s_cbranch_scc1 .LBB0_580

.LBB0_580:
	s_cmpk_gt_u32 s28, 0x17f
	s_cbranch_scc0 .LBB0_676
	s_cmpk_gt_u32 s28, 0x27f
	s_cbranch_scc0 .LBB0_605
	s_add_i32 s12, s28, 0xfffffd80
	s_and_saveexec_b64 s[4:5], s[38:39]
	s_cbranch_execz .Lon2_spun
	s_lshr_b32 s2, s12, 2
	s_and_b32 s2, s2, -4
	v_readlane_b32 s8, v255, 27
	s_add_u32 s8, s8, s2
	v_readlane_b32 s2, v255, 26
	s_addc_u32 s9, s2, 0
	v_mov_b64_e32 v[0:1], s[8:9]
	s_mov_b32 s2, 0
.Lon2_spin:
	global_load_dword v2, v[0:1], off sc1
	s_waitcnt vmcnt(0)
	v_readfirstlane_b32 s14, v2
	s_cmp_ge_u32 s14, 8
	s_cbranch_scc1 .Lon2_ready
	s_add_i32 s2, s2, 1
	s_cmp_lt_u32 s2, 0x1000000
	s_cbranch_scc0 .Lon2_ready
	s_sleep 2
	s_branch .Lon2_spin
.Lon2_ready:
	buffer_inv sc1
	s_waitcnt vmcnt(0)
.Lon2_spun:
	s_or_b64 exec, exec, s[4:5]
	s_waitcnt lgkmcnt(0)
	s_barrier
	s_load_dwordx2 s[8:9], s[0:1], 0xa8
	v_readlane_b32 s14, v255, 47
	v_readlane_b32 s15, v255, 48
	v_and_b32_e32 v11, 15, v228
	v_lshrrev_b32_e32 v12, 4, v228
	v_lshlrev_b32_e32 v13, 5, v11
	s_lshl_b32 s2, s12, 6
	s_and_b32 s2, s2, 0x7ffff000
	s_lshl_b32 s16, s12, 8
	s_and_b32 s16, s16, 0xf00
	s_or_b32 s2, s2, s16
	s_lshl_b32 s16, s12, 4
	s_and_b32 s16, s16, 0x300
	s_waitcnt lgkmcnt(0)
	s_add_u32 s8, s8, s14
	s_addc_u32 s9, s9, s15
	global_load_dwordx4 v[0:3], v13, s[8:9]
	global_load_dwordx4 v[4:7], v13, s[8:9] offset:16
	s_lshl_b32 s17, s2, 11
	s_lshl_b32 s18, s16, 1
	s_add_u32 s17, s17, s18
	s_add_u32 s14, s44, 0x150c0000
	s_addc_u32 s15, s45, 0
	s_add_u32 s14, s14, s17
	s_addc_u32 s15, s15, 0
	v_lshl_add_u32 v8, v12, 11, v13
	s_lshl_b32 s17, s2, 10
	s_add_u32 s17, s17, s16
	s_add_u32 s18, s44, 0x1b0c0000
	s_addc_u32 s19, s45, 0
	s_add_u32 s18, s18, s17
	s_addc_u32 s19, s19, 0
	v_lshlrev_b32_e32 v14, 4, v11
	v_lshl_add_u32 v10, v12, 10, v14
	s_mul_i32 s17, s2, 0x4600
	s_add_u32 s17, s17, s16
	s_add_u32 s16, s44, 0x38c1c00
	s_addc_u32 s9, s45, 0
	s_add_u32 s16, s16, s17
	s_addc_u32 s17, s9, 0
	v_mul_u32_u24_e32 v15, 0x4600, v12
	v_add_u32_e32 v9, v15, v14
	global_load_dwordx4 v[80:83], v8, s[14:15]
	global_load_dwordx4 v[84:87], v8, s[14:15] offset:16
	global_load_dwordx4 v[88:91], v9, s[16:17]
	s_add_u32 s14, s14, 0x10000
	s_addc_u32 s15, s15, 0
	s_add_u32 s16, s16, 0x8c000
	s_addc_u32 s17, s17, 0
	global_load_dwordx4 v[92:95], v8, s[14:15]
	global_load_dwordx4 v[96:99], v8, s[14:15] offset:16
	global_load_dwordx4 v[100:103], v9, s[16:17]
	s_add_u32 s14, s14, 0x10000
	s_addc_u32 s15, s15, 0
	s_add_u32 s16, s16, 0x8c000
	s_addc_u32 s17, s17, 0
	global_load_dwordx4 v[104:107], v8, s[14:15]
	global_load_dwordx4 v[108:111], v8, s[14:15] offset:16
	global_load_dwordx4 v[112:115], v9, s[16:17]
	s_add_u32 s14, s14, 0x10000
	s_addc_u32 s15, s15, 0
	s_add_u32 s16, s16, 0x8c000
	s_addc_u32 s17, s17, 0
	global_load_dwordx4 v[116:119], v8, s[14:15]
	global_load_dwordx4 v[120:123], v8, s[14:15] offset:16
	global_load_dwordx4 v[124:127], v9, s[16:17]
	s_add_u32 s14, s14, 0x10000
	s_addc_u32 s15, s15, 0
	s_add_u32 s16, s16, 0x8c000
	s_addc_u32 s17, s17, 0
	global_load_dwordx4 v[128:131], v8, s[14:15]
	global_load_dwordx4 v[132:135], v8, s[14:15] offset:16
	global_load_dwordx4 v[136:139], v9, s[16:17]
	s_add_u32 s14, s14, 0x10000
	s_addc_u32 s15, s15, 0
	s_add_u32 s16, s16, 0x8c000
	s_addc_u32 s17, s17, 0
	global_load_dwordx4 v[140:143], v8, s[14:15]
	global_load_dwordx4 v[144:147], v8, s[14:15] offset:16
	global_load_dwordx4 v[148:151], v9, s[16:17]
	s_add_u32 s14, s14, 0x10000
	s_addc_u32 s15, s15, 0
	s_add_u32 s16, s16, 0x8c000
	s_addc_u32 s17, s17, 0
	global_load_dwordx4 v[152:155], v8, s[14:15]
	global_load_dwordx4 v[156:159], v8, s[14:15] offset:16
	global_load_dwordx4 v[160:163], v9, s[16:17]
	s_add_u32 s14, s14, 0x10000
	s_addc_u32 s15, s15, 0
	s_add_u32 s16, s16, 0x8c000
	s_addc_u32 s17, s17, 0
	global_load_dwordx4 v[164:167], v8, s[14:15]
	global_load_dwordx4 v[168:171], v8, s[14:15] offset:16
	global_load_dwordx4 v[172:175], v9, s[16:17]
	s_waitcnt vmcnt(21)
	v_pk_mul_f32 v[36:37], v[80:81], v[80:81]
	v_pk_mul_f32 v[38:39], v[82:83], v[82:83]
	v_pk_mul_f32 v[40:41], v[84:85], v[84:85]
	v_pk_mul_f32 v[42:43], v[86:87], v[86:87]
	v_lshlrev_b32_e32 v28, 16, v88
	v_and_b32_e32 v29, 0xffff0000, v88
	v_lshlrev_b32_e32 v30, 16, v89
	v_and_b32_e32 v31, 0xffff0000, v89
	v_lshlrev_b32_e32 v32, 16, v90
	v_and_b32_e32 v33, 0xffff0000, v90
	v_lshlrev_b32_e32 v34, 16, v91
	v_and_b32_e32 v35, 0xffff0000, v91
	v_add_f32_e32 v36, v37, v36
	v_add_f32_e32 v38, v38, v39
	v_add_f32_e32 v40, v40, v41
	v_add_f32_e32 v42, v42, v43
	v_add_f32_e32 v36, v36, v38
	v_mul_f32_e32 v20, 0xbfb8aa3b, v28
	v_mul_f32_e32 v21, 0xbfb8aa3b, v29
	v_mul_f32_e32 v22, 0xbfb8aa3b, v30
	v_mul_f32_e32 v23, 0xbfb8aa3b, v31
	v_mul_f32_e32 v24, 0xbfb8aa3b, v32
	v_mul_f32_e32 v25, 0xbfb8aa3b, v33
	v_mul_f32_e32 v26, 0xbfb8aa3b, v34
	v_mul_f32_e32 v27, 0xbfb8aa3b, v35
	v_add_f32_e32 v36, v36, v40
	v_add_f32_e32 v36, v42, v36
	v_exp_f32_e32 v20, v20
	v_exp_f32_e32 v21, v21
	v_exp_f32_e32 v22, v22
	v_exp_f32_e32 v23, v23
	v_add_f32_dpp v36, v36, v36 quad_perm:[1,0,3,2] row_mask:0xf bank_mask:0xf
	v_exp_f32_e32 v24, v24
	v_exp_f32_e32 v25, v25
	v_exp_f32_e32 v26, v26
	v_exp_f32_e32 v27, v27
	v_add_f32_dpp v36, v36, v36 quad_perm:[2,3,0,1] row_mask:0xf bank_mask:0xf
	v_add_f32_e32 v20, 1.0, v20
	v_add_f32_e32 v21, 1.0, v21
	v_add_f32_e32 v22, 1.0, v22
	v_add_f32_e32 v23, 1.0, v23
	v_add_f32_dpp v36, v36, v36 row_half_mirror row_mask:0xf bank_mask:0xf
	v_add_f32_e32 v24, 1.0, v24
	v_add_f32_e32 v25, 1.0, v25
	v_add_f32_e32 v26, 1.0, v26
	v_add_f32_e32 v27, 1.0, v27
	v_add_f32_dpp v36, v36, v36 row_mirror row_mask:0xf bank_mask:0xf
	v_rcp_f32_e32 v20, v20
	v_rcp_f32_e32 v21, v21
	v_rcp_f32_e32 v22, v22
	v_rcp_f32_e32 v23, v23
	v_fmamk_f32 v36, v36, 0x3c000000, v231
	v_rcp_f32_e32 v24, v24
	v_rcp_f32_e32 v25, v25
	v_rcp_f32_e32 v26, v26
	v_rcp_f32_e32 v27, v27
	v_rsq_f32_e32 v36, v36
	v_mul_f32_e32 v20, v20, v28
	v_mul_f32_e32 v21, v21, v29
	v_mul_f32_e32 v22, v22, v30
	v_mul_f32_e32 v23, v23, v31
	v_mul_f32_e32 v24, v24, v32
	v_mul_f32_e32 v25, v25, v33
	v_mul_f32_e32 v26, v26, v34
	v_mul_f32_e32 v27, v27, v35
	v_mul_f32_e32 v28, v80, v36
	v_mul_f32_e32 v29, v81, v36
	v_mul_f32_e32 v30, v82, v36
	v_mul_f32_e32 v31, v83, v36
	v_mul_f32_e32 v32, v84, v36
	v_mul_f32_e32 v33, v85, v36
	v_mul_f32_e32 v34, v86, v36
	v_mul_f32_e32 v35, v87, v36
	v_mul_f32_e32 v28, v28, v0
	v_mul_f32_e32 v29, v29, v1
	v_mul_f32_e32 v30, v30, v2
	v_mul_f32_e32 v31, v31, v3
	v_mul_f32_e32 v32, v32, v4
	v_mul_f32_e32 v33, v33, v5
	v_mul_f32_e32 v34, v34, v6
	v_mul_f32_e32 v35, v35, v7
	v_mul_f32_e32 v28, v28, v20
	v_mul_f32_e32 v29, v29, v21
	v_mul_f32_e32 v30, v30, v22
	v_mul_f32_e32 v31, v31, v23
	v_mul_f32_e32 v32, v32, v24
	v_mul_f32_e32 v33, v33, v25
	v_mul_f32_e32 v34, v34, v26
	v_mul_f32_e32 v35, v35, v27
	v_cvt_pk_bf16_f32 v44, v28, v29
	v_cvt_pk_bf16_f32 v45, v30, v31
	v_cvt_pk_bf16_f32 v46, v32, v33
	v_cvt_pk_bf16_f32 v47, v34, v35
	global_store_dwordx4 v10, v[44:47], s[18:19]
	s_add_u32 s18, s18, 0x8000
	s_addc_u32 s19, s19, 0
	s_waitcnt vmcnt(19)
	v_pk_mul_f32 v[36:37], v[92:93], v[92:93]
	v_pk_mul_f32 v[38:39], v[94:95], v[94:95]
	v_pk_mul_f32 v[40:41], v[96:97], v[96:97]
	v_pk_mul_f32 v[42:43], v[98:99], v[98:99]
	v_lshlrev_b32_e32 v28, 16, v100
	v_and_b32_e32 v29, 0xffff0000, v100
	v_lshlrev_b32_e32 v30, 16, v101
	v_and_b32_e32 v31, 0xffff0000, v101
	v_lshlrev_b32_e32 v32, 16, v102
	v_and_b32_e32 v33, 0xffff0000, v102
	v_lshlrev_b32_e32 v34, 16, v103
	v_and_b32_e32 v35, 0xffff0000, v103
	v_add_f32_e32 v36, v37, v36
	v_add_f32_e32 v38, v38, v39
	v_add_f32_e32 v40, v40, v41
	v_add_f32_e32 v42, v42, v43
	v_add_f32_e32 v36, v36, v38
	v_mul_f32_e32 v20, 0xbfb8aa3b, v28
	v_mul_f32_e32 v21, 0xbfb8aa3b, v29
	v_mul_f32_e32 v22, 0xbfb8aa3b, v30
	v_mul_f32_e32 v23, 0xbfb8aa3b, v31
	v_mul_f32_e32 v24, 0xbfb8aa3b, v32
	v_mul_f32_e32 v25, 0xbfb8aa3b, v33
	v_mul_f32_e32 v26, 0xbfb8aa3b, v34
	v_mul_f32_e32 v27, 0xbfb8aa3b, v35
	v_add_f32_e32 v36, v36, v40
	v_add_f32_e32 v36, v42, v36
	v_exp_f32_e32 v20, v20
	v_exp_f32_e32 v21, v21
	v_exp_f32_e32 v22, v22
	v_exp_f32_e32 v23, v23
	v_add_f32_dpp v36, v36, v36 quad_perm:[1,0,3,2] row_mask:0xf bank_mask:0xf
	v_exp_f32_e32 v24, v24
	v_exp_f32_e32 v25, v25
	v_exp_f32_e32 v26, v26
	v_exp_f32_e32 v27, v27
	v_add_f32_dpp v36, v36, v36 quad_perm:[2,3,0,1] row_mask:0xf bank_mask:0xf
	v_add_f32_e32 v20, 1.0, v20
	v_add_f32_e32 v21, 1.0, v21
	v_add_f32_e32 v22, 1.0, v22
	v_add_f32_e32 v23, 1.0, v23
	v_add_f32_dpp v36, v36, v36 row_half_mirror row_mask:0xf bank_mask:0xf
	v_add_f32_e32 v24, 1.0, v24
	v_add_f32_e32 v25, 1.0, v25
	v_add_f32_e32 v26, 1.0, v26
	v_add_f32_e32 v27, 1.0, v27
	v_add_f32_dpp v36, v36, v36 row_mirror row_mask:0xf bank_mask:0xf
	v_rcp_f32_e32 v20, v20
	v_rcp_f32_e32 v21, v21
	v_rcp_f32_e32 v22, v22
	v_rcp_f32_e32 v23, v23
	v_fmamk_f32 v36, v36, 0x3c000000, v231
	v_rcp_f32_e32 v24, v24
	v_rcp_f32_e32 v25, v25
	v_rcp_f32_e32 v26, v26
	v_rcp_f32_e32 v27, v27
	v_rsq_f32_e32 v36, v36
	v_mul_f32_e32 v20, v20, v28
	v_mul_f32_e32 v21, v21, v29
	v_mul_f32_e32 v22, v22, v30
	v_mul_f32_e32 v23, v23, v31
	v_mul_f32_e32 v24, v24, v32
	v_mul_f32_e32 v25, v25, v33
	v_mul_f32_e32 v26, v26, v34
	v_mul_f32_e32 v27, v27, v35
	v_mul_f32_e32 v28, v92, v36
	v_mul_f32_e32 v29, v93, v36
	v_mul_f32_e32 v30, v94, v36
	v_mul_f32_e32 v31, v95, v36
	v_mul_f32_e32 v32, v96, v36
	v_mul_f32_e32 v33, v97, v36
	v_mul_f32_e32 v34, v98, v36
	v_mul_f32_e32 v35, v99, v36
	v_mul_f32_e32 v28, v28, v0
	v_mul_f32_e32 v29, v29, v1
	v_mul_f32_e32 v30, v30, v2
	v_mul_f32_e32 v31, v31, v3
	v_mul_f32_e32 v32, v32, v4
	v_mul_f32_e32 v33, v33, v5
	v_mul_f32_e32 v34, v34, v6
	v_mul_f32_e32 v35, v35, v7
	v_mul_f32_e32 v28, v28, v20
	v_mul_f32_e32 v29, v29, v21
	v_mul_f32_e32 v30, v30, v22
	v_mul_f32_e32 v31, v31, v23
	v_mul_f32_e32 v32, v32, v24
	v_mul_f32_e32 v33, v33, v25
	v_mul_f32_e32 v34, v34, v26
	v_mul_f32_e32 v35, v35, v27
	v_cvt_pk_bf16_f32 v44, v28, v29
	v_cvt_pk_bf16_f32 v45, v30, v31
	v_cvt_pk_bf16_f32 v46, v32, v33
	v_cvt_pk_bf16_f32 v47, v34, v35
	global_store_dwordx4 v10, v[44:47], s[18:19]
	s_add_u32 s18, s18, 0x8000
	s_addc_u32 s19, s19, 0
	s_waitcnt vmcnt(17)
	v_pk_mul_f32 v[36:37], v[104:105], v[104:105]
	v_pk_mul_f32 v[38:39], v[106:107], v[106:107]
	v_pk_mul_f32 v[40:41], v[108:109], v[108:109]
	v_pk_mul_f32 v[42:43], v[110:111], v[110:111]
	v_lshlrev_b32_e32 v28, 16, v112
	v_and_b32_e32 v29, 0xffff0000, v112
	v_lshlrev_b32_e32 v30, 16, v113
	v_and_b32_e32 v31, 0xffff0000, v113
	v_lshlrev_b32_e32 v32, 16, v114
	v_and_b32_e32 v33, 0xffff0000, v114
	v_lshlrev_b32_e32 v34, 16, v115
	v_and_b32_e32 v35, 0xffff0000, v115
	v_add_f32_e32 v36, v37, v36
	v_add_f32_e32 v38, v38, v39
	v_add_f32_e32 v40, v40, v41
	v_add_f32_e32 v42, v42, v43
	v_add_f32_e32 v36, v36, v38
	v_mul_f32_e32 v20, 0xbfb8aa3b, v28
	v_mul_f32_e32 v21, 0xbfb8aa3b, v29
	v_mul_f32_e32 v22, 0xbfb8aa3b, v30
	v_mul_f32_e32 v23, 0xbfb8aa3b, v31
	v_mul_f32_e32 v24, 0xbfb8aa3b, v32
	v_mul_f32_e32 v25, 0xbfb8aa3b, v33
	v_mul_f32_e32 v26, 0xbfb8aa3b, v34
	v_mul_f32_e32 v27, 0xbfb8aa3b, v35
	v_add_f32_e32 v36, v36, v40
	v_add_f32_e32 v36, v42, v36
	v_exp_f32_e32 v20, v20
	v_exp_f32_e32 v21, v21
	v_exp_f32_e32 v22, v22
	v_exp_f32_e32 v23, v23
	v_add_f32_dpp v36, v36, v36 quad_perm:[1,0,3,2] row_mask:0xf bank_mask:0xf
	v_exp_f32_e32 v24, v24
	v_exp_f32_e32 v25, v25
	v_exp_f32_e32 v26, v26
	v_exp_f32_e32 v27, v27
	v_add_f32_dpp v36, v36, v36 quad_perm:[2,3,0,1] row_mask:0xf bank_mask:0xf
	v_add_f32_e32 v20, 1.0, v20
	v_add_f32_e32 v21, 1.0, v21
	v_add_f32_e32 v22, 1.0, v22
	v_add_f32_e32 v23, 1.0, v23
	v_add_f32_dpp v36, v36, v36 row_half_mirror row_mask:0xf bank_mask:0xf
	v_add_f32_e32 v24, 1.0, v24
	v_add_f32_e32 v25, 1.0, v25
	v_add_f32_e32 v26, 1.0, v26
	v_add_f32_e32 v27, 1.0, v27
	v_add_f32_dpp v36, v36, v36 row_mirror row_mask:0xf bank_mask:0xf
	v_rcp_f32_e32 v20, v20
	v_rcp_f32_e32 v21, v21
	v_rcp_f32_e32 v22, v22
	v_rcp_f32_e32 v23, v23
	v_fmamk_f32 v36, v36, 0x3c000000, v231
	v_rcp_f32_e32 v24, v24
	v_rcp_f32_e32 v25, v25
	v_rcp_f32_e32 v26, v26
	v_rcp_f32_e32 v27, v27
	v_rsq_f32_e32 v36, v36
	v_mul_f32_e32 v20, v20, v28
	v_mul_f32_e32 v21, v21, v29
	v_mul_f32_e32 v22, v22, v30
	v_mul_f32_e32 v23, v23, v31
	v_mul_f32_e32 v24, v24, v32
	v_mul_f32_e32 v25, v25, v33
	v_mul_f32_e32 v26, v26, v34
	v_mul_f32_e32 v27, v27, v35
	v_mul_f32_e32 v28, v104, v36
	v_mul_f32_e32 v29, v105, v36
	v_mul_f32_e32 v30, v106, v36
	v_mul_f32_e32 v31, v107, v36
	v_mul_f32_e32 v32, v108, v36
	v_mul_f32_e32 v33, v109, v36
	v_mul_f32_e32 v34, v110, v36
	v_mul_f32_e32 v35, v111, v36
	v_mul_f32_e32 v28, v28, v0
	v_mul_f32_e32 v29, v29, v1
	v_mul_f32_e32 v30, v30, v2
	v_mul_f32_e32 v31, v31, v3
	v_mul_f32_e32 v32, v32, v4
	v_mul_f32_e32 v33, v33, v5
	v_mul_f32_e32 v34, v34, v6
	v_mul_f32_e32 v35, v35, v7
	v_mul_f32_e32 v28, v28, v20
	v_mul_f32_e32 v29, v29, v21
	v_mul_f32_e32 v30, v30, v22
	v_mul_f32_e32 v31, v31, v23
	v_mul_f32_e32 v32, v32, v24
	v_mul_f32_e32 v33, v33, v25
	v_mul_f32_e32 v34, v34, v26
	v_mul_f32_e32 v35, v35, v27
	v_cvt_pk_bf16_f32 v44, v28, v29
	v_cvt_pk_bf16_f32 v45, v30, v31
	v_cvt_pk_bf16_f32 v46, v32, v33
	v_cvt_pk_bf16_f32 v47, v34, v35
	global_store_dwordx4 v10, v[44:47], s[18:19]
	s_add_u32 s18, s18, 0x8000
	s_addc_u32 s19, s19, 0
	s_waitcnt vmcnt(15)
	v_pk_mul_f32 v[36:37], v[116:117], v[116:117]
	v_pk_mul_f32 v[38:39], v[118:119], v[118:119]
	v_pk_mul_f32 v[40:41], v[120:121], v[120:121]
	v_pk_mul_f32 v[42:43], v[122:123], v[122:123]
	v_lshlrev_b32_e32 v28, 16, v124
	v_and_b32_e32 v29, 0xffff0000, v124
	v_lshlrev_b32_e32 v30, 16, v125
	v_and_b32_e32 v31, 0xffff0000, v125
	v_lshlrev_b32_e32 v32, 16, v126
	v_and_b32_e32 v33, 0xffff0000, v126
	v_lshlrev_b32_e32 v34, 16, v127
	v_and_b32_e32 v35, 0xffff0000, v127
	v_add_f32_e32 v36, v37, v36
	v_add_f32_e32 v38, v38, v39
	v_add_f32_e32 v40, v40, v41
	v_add_f32_e32 v42, v42, v43
	v_add_f32_e32 v36, v36, v38
	v_mul_f32_e32 v20, 0xbfb8aa3b, v28
	v_mul_f32_e32 v21, 0xbfb8aa3b, v29
	v_mul_f32_e32 v22, 0xbfb8aa3b, v30
	v_mul_f32_e32 v23, 0xbfb8aa3b, v31
	v_mul_f32_e32 v24, 0xbfb8aa3b, v32
	v_mul_f32_e32 v25, 0xbfb8aa3b, v33
	v_mul_f32_e32 v26, 0xbfb8aa3b, v34
	v_mul_f32_e32 v27, 0xbfb8aa3b, v35
	v_add_f32_e32 v36, v36, v40
	v_add_f32_e32 v36, v42, v36
	v_exp_f32_e32 v20, v20
	v_exp_f32_e32 v21, v21
	v_exp_f32_e32 v22, v22
	v_exp_f32_e32 v23, v23
	v_add_f32_dpp v36, v36, v36 quad_perm:[1,0,3,2] row_mask:0xf bank_mask:0xf
	v_exp_f32_e32 v24, v24
	v_exp_f32_e32 v25, v25
	v_exp_f32_e32 v26, v26
	v_exp_f32_e32 v27, v27
	v_add_f32_dpp v36, v36, v36 quad_perm:[2,3,0,1] row_mask:0xf bank_mask:0xf
	v_add_f32_e32 v20, 1.0, v20
	v_add_f32_e32 v21, 1.0, v21
	v_add_f32_e32 v22, 1.0, v22
	v_add_f32_e32 v23, 1.0, v23
	v_add_f32_dpp v36, v36, v36 row_half_mirror row_mask:0xf bank_mask:0xf
	v_add_f32_e32 v24, 1.0, v24
	v_add_f32_e32 v25, 1.0, v25
	v_add_f32_e32 v26, 1.0, v26
	v_add_f32_e32 v27, 1.0, v27
	v_add_f32_dpp v36, v36, v36 row_mirror row_mask:0xf bank_mask:0xf
	v_rcp_f32_e32 v20, v20
	v_rcp_f32_e32 v21, v21
	v_rcp_f32_e32 v22, v22
	v_rcp_f32_e32 v23, v23
	v_fmamk_f32 v36, v36, 0x3c000000, v231
	v_rcp_f32_e32 v24, v24
	v_rcp_f32_e32 v25, v25
	v_rcp_f32_e32 v26, v26
	v_rcp_f32_e32 v27, v27
	v_rsq_f32_e32 v36, v36
	v_mul_f32_e32 v20, v20, v28
	v_mul_f32_e32 v21, v21, v29
	v_mul_f32_e32 v22, v22, v30
	v_mul_f32_e32 v23, v23, v31
	v_mul_f32_e32 v24, v24, v32
	v_mul_f32_e32 v25, v25, v33
	v_mul_f32_e32 v26, v26, v34
	v_mul_f32_e32 v27, v27, v35
	v_mul_f32_e32 v28, v116, v36
	v_mul_f32_e32 v29, v117, v36
	v_mul_f32_e32 v30, v118, v36
	v_mul_f32_e32 v31, v119, v36
	v_mul_f32_e32 v32, v120, v36
	v_mul_f32_e32 v33, v121, v36
	v_mul_f32_e32 v34, v122, v36
	v_mul_f32_e32 v35, v123, v36
	v_mul_f32_e32 v28, v28, v0
	v_mul_f32_e32 v29, v29, v1
	v_mul_f32_e32 v30, v30, v2
	v_mul_f32_e32 v31, v31, v3
	v_mul_f32_e32 v32, v32, v4
	v_mul_f32_e32 v33, v33, v5
	v_mul_f32_e32 v34, v34, v6
	v_mul_f32_e32 v35, v35, v7
	v_mul_f32_e32 v28, v28, v20
	v_mul_f32_e32 v29, v29, v21
	v_mul_f32_e32 v30, v30, v22
	v_mul_f32_e32 v31, v31, v23
	v_mul_f32_e32 v32, v32, v24
	v_mul_f32_e32 v33, v33, v25
	v_mul_f32_e32 v34, v34, v26
	v_mul_f32_e32 v35, v35, v27
	v_cvt_pk_bf16_f32 v44, v28, v29
	v_cvt_pk_bf16_f32 v45, v30, v31
	v_cvt_pk_bf16_f32 v46, v32, v33
	v_cvt_pk_bf16_f32 v47, v34, v35
	global_store_dwordx4 v10, v[44:47], s[18:19]
	s_add_u32 s18, s18, 0x8000
	s_addc_u32 s19, s19, 0
	s_waitcnt vmcnt(13)
	v_pk_mul_f32 v[36:37], v[128:129], v[128:129]
	v_pk_mul_f32 v[38:39], v[130:131], v[130:131]
	v_pk_mul_f32 v[40:41], v[132:133], v[132:133]
	v_pk_mul_f32 v[42:43], v[134:135], v[134:135]
	v_lshlrev_b32_e32 v28, 16, v136
	v_and_b32_e32 v29, 0xffff0000, v136
	v_lshlrev_b32_e32 v30, 16, v137
	v_and_b32_e32 v31, 0xffff0000, v137
	v_lshlrev_b32_e32 v32, 16, v138
	v_and_b32_e32 v33, 0xffff0000, v138
	v_lshlrev_b32_e32 v34, 16, v139
	v_and_b32_e32 v35, 0xffff0000, v139
	v_add_f32_e32 v36, v37, v36
	v_add_f32_e32 v38, v38, v39
	v_add_f32_e32 v40, v40, v41
	v_add_f32_e32 v42, v42, v43
	v_add_f32_e32 v36, v36, v38
	v_mul_f32_e32 v20, 0xbfb8aa3b, v28
	v_mul_f32_e32 v21, 0xbfb8aa3b, v29
	v_mul_f32_e32 v22, 0xbfb8aa3b, v30
	v_mul_f32_e32 v23, 0xbfb8aa3b, v31
	v_mul_f32_e32 v24, 0xbfb8aa3b, v32
	v_mul_f32_e32 v25, 0xbfb8aa3b, v33
	v_mul_f32_e32 v26, 0xbfb8aa3b, v34
	v_mul_f32_e32 v27, 0xbfb8aa3b, v35
	v_add_f32_e32 v36, v36, v40
	v_add_f32_e32 v36, v42, v36
	v_exp_f32_e32 v20, v20
	v_exp_f32_e32 v21, v21
	v_exp_f32_e32 v22, v22
	v_exp_f32_e32 v23, v23
	v_add_f32_dpp v36, v36, v36 quad_perm:[1,0,3,2] row_mask:0xf bank_mask:0xf
	v_exp_f32_e32 v24, v24
	v_exp_f32_e32 v25, v25
	v_exp_f32_e32 v26, v26
	v_exp_f32_e32 v27, v27
	v_add_f32_dpp v36, v36, v36 quad_perm:[2,3,0,1] row_mask:0xf bank_mask:0xf
	v_add_f32_e32 v20, 1.0, v20
	v_add_f32_e32 v21, 1.0, v21
	v_add_f32_e32 v22, 1.0, v22
	v_add_f32_e32 v23, 1.0, v23
	v_add_f32_dpp v36, v36, v36 row_half_mirror row_mask:0xf bank_mask:0xf
	v_add_f32_e32 v24, 1.0, v24
	v_add_f32_e32 v25, 1.0, v25
	v_add_f32_e32 v26, 1.0, v26
	v_add_f32_e32 v27, 1.0, v27
	v_add_f32_dpp v36, v36, v36 row_mirror row_mask:0xf bank_mask:0xf
	v_rcp_f32_e32 v20, v20
	v_rcp_f32_e32 v21, v21
	v_rcp_f32_e32 v22, v22
	v_rcp_f32_e32 v23, v23
	v_fmamk_f32 v36, v36, 0x3c000000, v231
	v_rcp_f32_e32 v24, v24
	v_rcp_f32_e32 v25, v25
	v_rcp_f32_e32 v26, v26
	v_rcp_f32_e32 v27, v27
	v_rsq_f32_e32 v36, v36
	v_mul_f32_e32 v20, v20, v28
	v_mul_f32_e32 v21, v21, v29
	v_mul_f32_e32 v22, v22, v30
	v_mul_f32_e32 v23, v23, v31
	v_mul_f32_e32 v24, v24, v32
	v_mul_f32_e32 v25, v25, v33
	v_mul_f32_e32 v26, v26, v34
	v_mul_f32_e32 v27, v27, v35
	v_mul_f32_e32 v28, v128, v36
	v_mul_f32_e32 v29, v129, v36
	v_mul_f32_e32 v30, v130, v36
	v_mul_f32_e32 v31, v131, v36
	v_mul_f32_e32 v32, v132, v36
	v_mul_f32_e32 v33, v133, v36
	v_mul_f32_e32 v34, v134, v36
	v_mul_f32_e32 v35, v135, v36
	v_mul_f32_e32 v28, v28, v0
	v_mul_f32_e32 v29, v29, v1
	v_mul_f32_e32 v30, v30, v2
	v_mul_f32_e32 v31, v31, v3
	v_mul_f32_e32 v32, v32, v4
	v_mul_f32_e32 v33, v33, v5
	v_mul_f32_e32 v34, v34, v6
	v_mul_f32_e32 v35, v35, v7
	v_mul_f32_e32 v28, v28, v20
	v_mul_f32_e32 v29, v29, v21
	v_mul_f32_e32 v30, v30, v22
	v_mul_f32_e32 v31, v31, v23
	v_mul_f32_e32 v32, v32, v24
	v_mul_f32_e32 v33, v33, v25
	v_mul_f32_e32 v34, v34, v26
	v_mul_f32_e32 v35, v35, v27
	v_cvt_pk_bf16_f32 v44, v28, v29
	v_cvt_pk_bf16_f32 v45, v30, v31
	v_cvt_pk_bf16_f32 v46, v32, v33
	v_cvt_pk_bf16_f32 v47, v34, v35
	global_store_dwordx4 v10, v[44:47], s[18:19]
	s_add_u32 s18, s18, 0x8000
	s_addc_u32 s19, s19, 0
	s_waitcnt vmcnt(11)
	v_pk_mul_f32 v[36:37], v[140:141], v[140:141]
	v_pk_mul_f32 v[38:39], v[142:143], v[142:143]
	v_pk_mul_f32 v[40:41], v[144:145], v[144:145]
	v_pk_mul_f32 v[42:43], v[146:147], v[146:147]
	v_lshlrev_b32_e32 v28, 16, v148
	v_and_b32_e32 v29, 0xffff0000, v148
	v_lshlrev_b32_e32 v30, 16, v149
	v_and_b32_e32 v31, 0xffff0000, v149
	v_lshlrev_b32_e32 v32, 16, v150
	v_and_b32_e32 v33, 0xffff0000, v150
	v_lshlrev_b32_e32 v34, 16, v151
	v_and_b32_e32 v35, 0xffff0000, v151
	v_add_f32_e32 v36, v37, v36
	v_add_f32_e32 v38, v38, v39
	v_add_f32_e32 v40, v40, v41
	v_add_f32_e32 v42, v42, v43
	v_add_f32_e32 v36, v36, v38
	v_mul_f32_e32 v20, 0xbfb8aa3b, v28
	v_mul_f32_e32 v21, 0xbfb8aa3b, v29
	v_mul_f32_e32 v22, 0xbfb8aa3b, v30
	v_mul_f32_e32 v23, 0xbfb8aa3b, v31
	v_mul_f32_e32 v24, 0xbfb8aa3b, v32
	v_mul_f32_e32 v25, 0xbfb8aa3b, v33
	v_mul_f32_e32 v26, 0xbfb8aa3b, v34
	v_mul_f32_e32 v27, 0xbfb8aa3b, v35
	v_add_f32_e32 v36, v36, v40
	v_add_f32_e32 v36, v42, v36
	v_exp_f32_e32 v20, v20
	v_exp_f32_e32 v21, v21
	v_exp_f32_e32 v22, v22
	v_exp_f32_e32 v23, v23
	v_add_f32_dpp v36, v36, v36 quad_perm:[1,0,3,2] row_mask:0xf bank_mask:0xf
	v_exp_f32_e32 v24, v24
	v_exp_f32_e32 v25, v25
	v_exp_f32_e32 v26, v26
	v_exp_f32_e32 v27, v27
	v_add_f32_dpp v36, v36, v36 quad_perm:[2,3,0,1] row_mask:0xf bank_mask:0xf
	v_add_f32_e32 v20, 1.0, v20
	v_add_f32_e32 v21, 1.0, v21
	v_add_f32_e32 v22, 1.0, v22
	v_add_f32_e32 v23, 1.0, v23
	v_add_f32_dpp v36, v36, v36 row_half_mirror row_mask:0xf bank_mask:0xf
	v_add_f32_e32 v24, 1.0, v24
	v_add_f32_e32 v25, 1.0, v25
	v_add_f32_e32 v26, 1.0, v26
	v_add_f32_e32 v27, 1.0, v27
	v_add_f32_dpp v36, v36, v36 row_mirror row_mask:0xf bank_mask:0xf
	v_rcp_f32_e32 v20, v20
	v_rcp_f32_e32 v21, v21
	v_rcp_f32_e32 v22, v22
	v_rcp_f32_e32 v23, v23
	v_fmamk_f32 v36, v36, 0x3c000000, v231
	v_rcp_f32_e32 v24, v24
	v_rcp_f32_e32 v25, v25
	v_rcp_f32_e32 v26, v26
	v_rcp_f32_e32 v27, v27
	v_rsq_f32_e32 v36, v36
	v_mul_f32_e32 v20, v20, v28
	v_mul_f32_e32 v21, v21, v29
	v_mul_f32_e32 v22, v22, v30
	v_mul_f32_e32 v23, v23, v31
	v_mul_f32_e32 v24, v24, v32
	v_mul_f32_e32 v25, v25, v33
	v_mul_f32_e32 v26, v26, v34
	v_mul_f32_e32 v27, v27, v35
	v_mul_f32_e32 v28, v140, v36
	v_mul_f32_e32 v29, v141, v36
	v_mul_f32_e32 v30, v142, v36
	v_mul_f32_e32 v31, v143, v36
	v_mul_f32_e32 v32, v144, v36
	v_mul_f32_e32 v33, v145, v36
	v_mul_f32_e32 v34, v146, v36
	v_mul_f32_e32 v35, v147, v36
	v_mul_f32_e32 v28, v28, v0
	v_mul_f32_e32 v29, v29, v1
	v_mul_f32_e32 v30, v30, v2
	v_mul_f32_e32 v31, v31, v3
	v_mul_f32_e32 v32, v32, v4
	v_mul_f32_e32 v33, v33, v5
	v_mul_f32_e32 v34, v34, v6
	v_mul_f32_e32 v35, v35, v7
	v_mul_f32_e32 v28, v28, v20
	v_mul_f32_e32 v29, v29, v21
	v_mul_f32_e32 v30, v30, v22
	v_mul_f32_e32 v31, v31, v23
	v_mul_f32_e32 v32, v32, v24
	v_mul_f32_e32 v33, v33, v25
	v_mul_f32_e32 v34, v34, v26
	v_mul_f32_e32 v35, v35, v27
	v_cvt_pk_bf16_f32 v44, v28, v29
	v_cvt_pk_bf16_f32 v45, v30, v31
	v_cvt_pk_bf16_f32 v46, v32, v33
	v_cvt_pk_bf16_f32 v47, v34, v35
	global_store_dwordx4 v10, v[44:47], s[18:19]
	s_add_u32 s18, s18, 0x8000
	s_addc_u32 s19, s19, 0
	s_waitcnt vmcnt(9)
	v_pk_mul_f32 v[36:37], v[152:153], v[152:153]
	v_pk_mul_f32 v[38:39], v[154:155], v[154:155]
	v_pk_mul_f32 v[40:41], v[156:157], v[156:157]
	v_pk_mul_f32 v[42:43], v[158:159], v[158:159]
	v_lshlrev_b32_e32 v28, 16, v160
	v_and_b32_e32 v29, 0xffff0000, v160
	v_lshlrev_b32_e32 v30, 16, v161
	v_and_b32_e32 v31, 0xffff0000, v161
	v_lshlrev_b32_e32 v32, 16, v162
	v_and_b32_e32 v33, 0xffff0000, v162
	v_lshlrev_b32_e32 v34, 16, v163
	v_and_b32_e32 v35, 0xffff0000, v163
	v_add_f32_e32 v36, v37, v36
	v_add_f32_e32 v38, v38, v39
	v_add_f32_e32 v40, v40, v41
	v_add_f32_e32 v42, v42, v43
	v_add_f32_e32 v36, v36, v38
	v_mul_f32_e32 v20, 0xbfb8aa3b, v28
	v_mul_f32_e32 v21, 0xbfb8aa3b, v29
	v_mul_f32_e32 v22, 0xbfb8aa3b, v30
	v_mul_f32_e32 v23, 0xbfb8aa3b, v31
	v_mul_f32_e32 v24, 0xbfb8aa3b, v32
	v_mul_f32_e32 v25, 0xbfb8aa3b, v33
	v_mul_f32_e32 v26, 0xbfb8aa3b, v34
	v_mul_f32_e32 v27, 0xbfb8aa3b, v35
	v_add_f32_e32 v36, v36, v40
	v_add_f32_e32 v36, v42, v36
	v_exp_f32_e32 v20, v20
	v_exp_f32_e32 v21, v21
	v_exp_f32_e32 v22, v22
	v_exp_f32_e32 v23, v23
	v_add_f32_dpp v36, v36, v36 quad_perm:[1,0,3,2] row_mask:0xf bank_mask:0xf
	v_exp_f32_e32 v24, v24
	v_exp_f32_e32 v25, v25
	v_exp_f32_e32 v26, v26
	v_exp_f32_e32 v27, v27
	v_add_f32_dpp v36, v36, v36 quad_perm:[2,3,0,1] row_mask:0xf bank_mask:0xf
	v_add_f32_e32 v20, 1.0, v20
	v_add_f32_e32 v21, 1.0, v21
	v_add_f32_e32 v22, 1.0, v22
	v_add_f32_e32 v23, 1.0, v23
	v_add_f32_dpp v36, v36, v36 row_half_mirror row_mask:0xf bank_mask:0xf
	v_add_f32_e32 v24, 1.0, v24
	v_add_f32_e32 v25, 1.0, v25
	v_add_f32_e32 v26, 1.0, v26
	v_add_f32_e32 v27, 1.0, v27
	v_add_f32_dpp v36, v36, v36 row_mirror row_mask:0xf bank_mask:0xf
	v_rcp_f32_e32 v20, v20
	v_rcp_f32_e32 v21, v21
	v_rcp_f32_e32 v22, v22
	v_rcp_f32_e32 v23, v23
	v_fmamk_f32 v36, v36, 0x3c000000, v231
	v_rcp_f32_e32 v24, v24
	v_rcp_f32_e32 v25, v25
	v_rcp_f32_e32 v26, v26
	v_rcp_f32_e32 v27, v27
	v_rsq_f32_e32 v36, v36
	v_mul_f32_e32 v20, v20, v28
	v_mul_f32_e32 v21, v21, v29
	v_mul_f32_e32 v22, v22, v30
	v_mul_f32_e32 v23, v23, v31
	v_mul_f32_e32 v24, v24, v32
	v_mul_f32_e32 v25, v25, v33
	v_mul_f32_e32 v26, v26, v34
	v_mul_f32_e32 v27, v27, v35
	v_mul_f32_e32 v28, v152, v36
	v_mul_f32_e32 v29, v153, v36
	v_mul_f32_e32 v30, v154, v36
	v_mul_f32_e32 v31, v155, v36
	v_mul_f32_e32 v32, v156, v36
	v_mul_f32_e32 v33, v157, v36
	v_mul_f32_e32 v34, v158, v36
	v_mul_f32_e32 v35, v159, v36
	v_mul_f32_e32 v28, v28, v0
	v_mul_f32_e32 v29, v29, v1
	v_mul_f32_e32 v30, v30, v2
	v_mul_f32_e32 v31, v31, v3
	v_mul_f32_e32 v32, v32, v4
	v_mul_f32_e32 v33, v33, v5
	v_mul_f32_e32 v34, v34, v6
	v_mul_f32_e32 v35, v35, v7
	v_mul_f32_e32 v28, v28, v20
	v_mul_f32_e32 v29, v29, v21
	v_mul_f32_e32 v30, v30, v22
	v_mul_f32_e32 v31, v31, v23
	v_mul_f32_e32 v32, v32, v24
	v_mul_f32_e32 v33, v33, v25
	v_mul_f32_e32 v34, v34, v26
	v_mul_f32_e32 v35, v35, v27
	v_cvt_pk_bf16_f32 v44, v28, v29
	v_cvt_pk_bf16_f32 v45, v30, v31
	v_cvt_pk_bf16_f32 v46, v32, v33
	v_cvt_pk_bf16_f32 v47, v34, v35
	global_store_dwordx4 v10, v[44:47], s[18:19]
	s_add_u32 s18, s18, 0x8000
	s_addc_u32 s19, s19, 0
	s_waitcnt vmcnt(7)
	v_pk_mul_f32 v[36:37], v[164:165], v[164:165]
	v_pk_mul_f32 v[38:39], v[166:167], v[166:167]
	v_pk_mul_f32 v[40:41], v[168:169], v[168:169]
	v_pk_mul_f32 v[42:43], v[170:171], v[170:171]
	v_lshlrev_b32_e32 v28, 16, v172
	v_and_b32_e32 v29, 0xffff0000, v172
	v_lshlrev_b32_e32 v30, 16, v173
	v_and_b32_e32 v31, 0xffff0000, v173
	v_lshlrev_b32_e32 v32, 16, v174
	v_and_b32_e32 v33, 0xffff0000, v174
	v_lshlrev_b32_e32 v34, 16, v175
	v_and_b32_e32 v35, 0xffff0000, v175
	v_add_f32_e32 v36, v37, v36
	v_add_f32_e32 v38, v38, v39
	v_add_f32_e32 v40, v40, v41
	v_add_f32_e32 v42, v42, v43
	v_add_f32_e32 v36, v36, v38
	v_mul_f32_e32 v20, 0xbfb8aa3b, v28
	v_mul_f32_e32 v21, 0xbfb8aa3b, v29
	v_mul_f32_e32 v22, 0xbfb8aa3b, v30
	v_mul_f32_e32 v23, 0xbfb8aa3b, v31
	v_mul_f32_e32 v24, 0xbfb8aa3b, v32
	v_mul_f32_e32 v25, 0xbfb8aa3b, v33
	v_mul_f32_e32 v26, 0xbfb8aa3b, v34
	v_mul_f32_e32 v27, 0xbfb8aa3b, v35
	v_add_f32_e32 v36, v36, v40
	v_add_f32_e32 v36, v42, v36
	v_exp_f32_e32 v20, v20
	v_exp_f32_e32 v21, v21
	v_exp_f32_e32 v22, v22
	v_exp_f32_e32 v23, v23
	v_add_f32_dpp v36, v36, v36 quad_perm:[1,0,3,2] row_mask:0xf bank_mask:0xf
	v_exp_f32_e32 v24, v24
	v_exp_f32_e32 v25, v25
	v_exp_f32_e32 v26, v26
	v_exp_f32_e32 v27, v27
	v_add_f32_dpp v36, v36, v36 quad_perm:[2,3,0,1] row_mask:0xf bank_mask:0xf
	v_add_f32_e32 v20, 1.0, v20
	v_add_f32_e32 v21, 1.0, v21
	v_add_f32_e32 v22, 1.0, v22
	v_add_f32_e32 v23, 1.0, v23
	v_add_f32_dpp v36, v36, v36 row_half_mirror row_mask:0xf bank_mask:0xf
	v_add_f32_e32 v24, 1.0, v24
	v_add_f32_e32 v25, 1.0, v25
	v_add_f32_e32 v26, 1.0, v26
	v_add_f32_e32 v27, 1.0, v27
	v_add_f32_dpp v36, v36, v36 row_mirror row_mask:0xf bank_mask:0xf
	v_rcp_f32_e32 v20, v20
	v_rcp_f32_e32 v21, v21
	v_rcp_f32_e32 v22, v22
	v_rcp_f32_e32 v23, v23
	v_fmamk_f32 v36, v36, 0x3c000000, v231
	v_rcp_f32_e32 v24, v24
	v_rcp_f32_e32 v25, v25
	v_rcp_f32_e32 v26, v26
	v_rcp_f32_e32 v27, v27
	v_rsq_f32_e32 v36, v36
	v_mul_f32_e32 v20, v20, v28
	v_mul_f32_e32 v21, v21, v29
	v_mul_f32_e32 v22, v22, v30
	v_mul_f32_e32 v23, v23, v31
	v_mul_f32_e32 v24, v24, v32
	v_mul_f32_e32 v25, v25, v33
	v_mul_f32_e32 v26, v26, v34
	v_mul_f32_e32 v27, v27, v35
	v_mul_f32_e32 v28, v164, v36
	v_mul_f32_e32 v29, v165, v36
	v_mul_f32_e32 v30, v166, v36
	v_mul_f32_e32 v31, v167, v36
	v_mul_f32_e32 v32, v168, v36
	v_mul_f32_e32 v33, v169, v36
	v_mul_f32_e32 v34, v170, v36
	v_mul_f32_e32 v35, v171, v36
	v_mul_f32_e32 v28, v28, v0
	v_mul_f32_e32 v29, v29, v1
	v_mul_f32_e32 v30, v30, v2
	v_mul_f32_e32 v31, v31, v3
	v_mul_f32_e32 v32, v32, v4
	v_mul_f32_e32 v33, v33, v5
	v_mul_f32_e32 v34, v34, v6
	v_mul_f32_e32 v35, v35, v7
	v_mul_f32_e32 v28, v28, v20
	v_mul_f32_e32 v29, v29, v21
	v_mul_f32_e32 v30, v30, v22
	v_mul_f32_e32 v31, v31, v23
	v_mul_f32_e32 v32, v32, v24
	v_mul_f32_e32 v33, v33, v25
	v_mul_f32_e32 v34, v34, v26
	v_mul_f32_e32 v35, v35, v27
	v_cvt_pk_bf16_f32 v44, v28, v29
	v_cvt_pk_bf16_f32 v45, v30, v31
	v_cvt_pk_bf16_f32 v46, v32, v33
	v_cvt_pk_bf16_f32 v47, v34, v35
	global_store_dwordx4 v10, v[44:47], s[18:19]
	s_mov_b64 s[4:5], 0
